# sync trims (race-free form): duplicate lgkmcnt(0) waits dropped in GEMM K-loops; GLA output unit-closing barrier dropped; GLA summary closing barrier moved to the loop exit edge
# speedup vs baseline: 1.0116x; 1.0071x over previous
; __device__ __forceinline__ void gla_summ_unit(const P& p, int unit, const SummRaw& raw) {
;     ...
; #pragma unroll 1
;   for (int tI = 0; tI < 8; ++tI) {
;     int tile = wid * 8 + tI;
;     int dir = tile >> 5, dkt = (tile >> 3) & 3, dvt = tile & 7;
;     const u16* Asrc = (dir ? kdbT : kdfT) + (dkt * 16 + fr) * LP + fq * 8;
;     const u16* Bsrc = vT + (dvt * 16 + fr) * LP + fq * 8;
;     f32x4 d = {0.f, 0.f, 0.f, 0.f};
; #pragma unroll
;     for (int ks = 0; ks < 2; ++ks) {
;       bf16x8 a = *(const bf16x8*)(Asrc + ks * 32);
;       bf16x8 b = *(const bf16x8*)(Bsrc + ks * 32);
;       d = __builtin_amdgcn_mfma_f32_16x16x32_bf16(a, b, d, 0, 0, 0);
;     }
;     uint2 w; w.x = pack2(d[0], d[1]); w.y = pack2(d[2], d[3]);
;     *(uint2*)(kvout + (size_t)(unit * 2 + dir) * 8192 + (dvt * 16 + fr) * 64 + dkt * 16 + fq * 4) = w;
;   }
; __device__ void phase_gla_summ(const P& p) {
;     ...
;   for (; u < 4096; u += gridDim.x) {
;     int un = u + gridDim.x;
;     SummRaw nxt = gla_summ_load(p, un < 4096 ? un : u, tid);
;     gla_summ_unit(p, u, cur);
;     cur = nxt;
;   }
.LBB0_227:
	v_add_u32_e32 v31, s0, v30
	v_add_u32_e32 v34, 0x11200, v31
	s_nop 0
	ds_read_b128 v[42:45], v34
	v_add_u32_e32 v31, 0x11240, v31
	ds_read_b128 v[52:55], v31
	s_addk_i32 s0, 0x900
	s_cmpk_lg_i32 s0, 0x4800
	s_waitcnt lgkmcnt(1)
	v_mfma_f32_16x16x32_bf16 v[42:45], v[8:11], v[42:45], 0
	s_waitcnt lgkmcnt(0)
	v_mfma_f32_16x16x32_bf16 v[42:45], v[12:15], v[52:55], v[42:45]
	s_nop 7
	v_cvt_pk_bf16_f32 v42, v42, v43
	v_cvt_pk_bf16_f32 v43, v44, v45
	global_store_dwordx2 v[28:29], v[42:43], off offset:-4
	v_lshl_add_u64 v[28:29], v[28:29], 0, s[22:23]
	s_cbranch_scc1 .LBB0_227
	s_waitcnt lgkmcnt(0)
	s_add_i32 s20, s20, s3
	s_andn2_b64 vcc, exec, s[24:25]
	s_mov_b32 s21, s46
	s_waitcnt vmcnt(3)
	v_mov_b64_e32 v[12:13], v[20:21]
	v_mov_b64_e32 v[14:15], v[22:23]
	s_waitcnt vmcnt(1)
	v_mov_b64_e32 v[8:9], v[24:25]
	v_mov_b64_e32 v[10:11], v[26:27]
	v_mov_b64_e32 v[28:29], v[16:17]
	v_mov_b64_e32 v[30:31], v[18:19]
	s_cbranch_vccnz .LBB0_224
	s_barrier
